# GEMM2 epilogue row sum-of-squares: xor-16 / xor-32 ds_bpermute steps replaced by v_permlane16_swap / v_permlane32_swap + add (no LDS round trips)
# baseline (speedup 1.0000x reference)
.LBB0_935:
	s_add_u32 s2, s12, 0xfffc0080
	s_addc_u32 s3, s13, -1
	s_add_i32 s38, 32, 0x10000
	v_add_u32_e32 v152, s38, v145
	ds_read_b128 v[140:143], v152
	ds_read_b128 v[148:151], v152 offset:1024
	ds_read_b128 v[164:167], v152 offset:2048
	ds_read_b128 v[168:171], v152 offset:3072
	s_cmp_eq_u32 vcc_hi, 12
	s_cselect_b32 s3, s31, s3
	s_cselect_b32 s2, s4, s2
	s_cselect_b32 s19, s11, s35
	s_cselect_b32 s18, vcc_lo, s34
	s_add_i32 m0, s14, 0xc000
	ds_read_b128 v[172:175], v147
	ds_read_b128 v[176:179], v147 offset:1024
	ds_read_b128 v[182:185], v147 offset:2048
	ds_read_b128 v[186:189], v147 offset:3072
	ds_read_b128 v[190:193], v147 offset:4096
	ds_read_b128 v[194:197], v147 offset:5120
	ds_read_b128 v[198:201], v147 offset:6144
	ds_read_b128 v[202:205], v147 offset:7168
	global_load_lds_dwordx4 v136, s[12:13]
	s_add_i32 m0, s14, 0xe000
	s_nop 0
	global_load_lds_dwordx4 v138, s[12:13]
	s_waitcnt lgkmcnt(8)
	s_barrier
	s_waitcnt lgkmcnt(0)
	s_waitcnt lgkmcnt(0)
	v_mfma_f32_16x16x32_bf16 v[126:129], v[140:143], v[172:175], v[126:129]
	v_mfma_f32_16x16x32_bf16 v[122:125], v[164:167], v[172:175], v[122:125]
	v_mfma_f32_16x16x32_bf16 v[110:113], v[140:143], v[182:185], v[110:113]
	v_mfma_f32_16x16x32_bf16 v[106:109], v[164:167], v[182:185], v[106:109]
	v_mfma_f32_16x16x32_bf16 v[94:97], v[140:143], v[190:193], v[94:97]
	v_mfma_f32_16x16x32_bf16 v[90:93], v[164:167], v[190:193], v[90:93]
	v_mfma_f32_16x16x32_bf16 v[78:81], v[140:143], v[198:201], v[78:81]
	v_mfma_f32_16x16x32_bf16 v[74:77], v[164:167], v[198:201], v[74:77]
	v_mfma_f32_16x16x32_bf16 v[126:129], v[148:151], v[176:179], v[126:129]
	v_mfma_f32_16x16x32_bf16 v[122:125], v[168:171], v[176:179], v[122:125]
	v_mfma_f32_16x16x32_bf16 v[110:113], v[148:151], v[186:189], v[110:113]
	v_mfma_f32_16x16x32_bf16 v[106:109], v[168:171], v[186:189], v[106:109]
	v_mfma_f32_16x16x32_bf16 v[94:97], v[148:151], v[194:197], v[94:97]
	v_mfma_f32_16x16x32_bf16 v[90:93], v[168:171], v[194:197], v[90:93]
	v_mfma_f32_16x16x32_bf16 v[78:81], v[148:151], v[202:205], v[78:81]
	v_mfma_f32_16x16x32_bf16 v[74:77], v[168:171], v[202:205], v[74:77]
	s_barrier
	s_add_i32 s24, 32, 0x14000
	s_add_i32 s38, s38, s7
	ds_read_b128 v[206:209], v152 offset:16384
	ds_read_b128 v[210:213], v152 offset:17408
	ds_read_b128 v[214:217], v152 offset:18432
	ds_read_b128 v[218:221], v152 offset:19456
	s_mov_b32 m0, s38
	s_nop 0
	global_load_lds_dwordx4 v154, s[18:19]
	s_add_i32 m0, s38, 0x2000
	s_nop 0
	global_load_lds_dwordx4 v130, s[18:19]
	s_barrier
	s_waitcnt lgkmcnt(0)
	s_waitcnt lgkmcnt(0)
	v_mfma_f32_16x16x32_bf16 v[118:121], v[206:209], v[172:175], v[118:121]
	v_mfma_f32_16x16x32_bf16 v[114:117], v[214:217], v[172:175], v[114:117]
	v_mfma_f32_16x16x32_bf16 v[102:105], v[206:209], v[182:185], v[102:105]
	v_mfma_f32_16x16x32_bf16 v[98:101], v[214:217], v[182:185], v[98:101]
	v_mfma_f32_16x16x32_bf16 v[86:89], v[206:209], v[190:193], v[86:89]
	v_mfma_f32_16x16x32_bf16 v[82:85], v[214:217], v[190:193], v[82:85]
	v_mfma_f32_16x16x32_bf16 v[70:73], v[206:209], v[198:201], v[70:73]
	v_mfma_f32_16x16x32_bf16 v[66:69], v[214:217], v[198:201], v[66:69]
	v_mfma_f32_16x16x32_bf16 v[118:121], v[210:213], v[176:179], v[118:121]
	v_mfma_f32_16x16x32_bf16 v[114:117], v[218:221], v[176:179], v[114:117]
	v_mfma_f32_16x16x32_bf16 v[102:105], v[210:213], v[186:189], v[102:105]
	v_mfma_f32_16x16x32_bf16 v[98:101], v[218:221], v[186:189], v[98:101]
	v_mfma_f32_16x16x32_bf16 v[86:89], v[210:213], v[194:197], v[86:89]
	v_mfma_f32_16x16x32_bf16 v[82:85], v[218:221], v[194:197], v[82:85]
	v_mfma_f32_16x16x32_bf16 v[70:73], v[210:213], v[202:205], v[70:73]
	v_mfma_f32_16x16x32_bf16 v[66:69], v[218:221], v[202:205], v[66:69]
	s_mov_b32 m0, s14
	s_mov_b64 s[98:99], s[2:3]
	s_barrier
	ds_read_b128 v[172:175], v147 offset:16384
	ds_read_b128 v[176:179], v147 offset:17408
	ds_read_b128 v[182:185], v147 offset:18432
	ds_read_b128 v[186:189], v147 offset:19456
	ds_read_b128 v[190:193], v147 offset:20480
	ds_read_b128 v[194:197], v147 offset:21504
	ds_read_b128 v[198:201], v147 offset:22528
	ds_read_b128 v[202:205], v147 offset:23552
	global_load_lds_dwordx4 v134, s[2:3]
	s_mov_b32 m0, s20
	s_nop 0
	global_load_lds_dwordx4 v132, s[2:3]
	s_barrier
	s_waitcnt lgkmcnt(0)
	s_waitcnt lgkmcnt(0)
	v_mfma_f32_16x16x32_bf16 v[62:65], v[140:143], v[172:175], v[62:65]
	v_mfma_f32_16x16x32_bf16 v[58:61], v[164:167], v[172:175], v[58:61]
	v_mfma_f32_16x16x32_bf16 v[46:49], v[140:143], v[182:185], v[46:49]
	v_mfma_f32_16x16x32_bf16 v[42:45], v[164:167], v[182:185], v[42:45]
	v_mfma_f32_16x16x32_bf16 v[30:33], v[140:143], v[190:193], v[30:33]
	v_mfma_f32_16x16x32_bf16 v[26:29], v[164:167], v[190:193], v[26:29]
	v_mfma_f32_16x16x32_bf16 v[14:17], v[140:143], v[198:201], v[14:17]
	v_mfma_f32_16x16x32_bf16 v[10:13], v[164:167], v[198:201], v[10:13]
	v_mfma_f32_16x16x32_bf16 v[62:65], v[148:151], v[176:179], v[62:65]
	v_mfma_f32_16x16x32_bf16 v[58:61], v[168:171], v[176:179], v[58:61]
	v_mfma_f32_16x16x32_bf16 v[46:49], v[148:151], v[186:189], v[46:49]
	v_mfma_f32_16x16x32_bf16 v[42:45], v[168:171], v[186:189], v[42:45]
	v_mfma_f32_16x16x32_bf16 v[30:33], v[148:151], v[194:197], v[30:33]
	v_mfma_f32_16x16x32_bf16 v[26:29], v[168:171], v[194:197], v[26:29]
	v_mfma_f32_16x16x32_bf16 v[14:17], v[148:151], v[202:205], v[14:17]
	v_mfma_f32_16x16x32_bf16 v[10:13], v[168:171], v[202:205], v[10:13]
	s_barrier
	s_add_u32 s38, s18, 0x40000
	s_addc_u32 s39, s19, 0
	s_add_i32 s24, s24, s7
	s_mov_b32 m0, s24
	s_nop 0
	global_load_lds_dwordx4 v154, s[38:39]
	s_add_i32 m0, s24, 0x2000
	s_nop 0
	global_load_lds_dwordx4 v130, s[38:39]
	s_waitcnt vmcnt(6)
	s_barrier
	v_mfma_f32_16x16x32_bf16 v[54:57], v[206:209], v[172:175], v[54:57]
	v_mfma_f32_16x16x32_bf16 v[50:53], v[214:217], v[172:175], v[50:53]
	v_mfma_f32_16x16x32_bf16 v[38:41], v[206:209], v[182:185], v[38:41]
	v_mfma_f32_16x16x32_bf16 v[34:37], v[214:217], v[182:185], v[34:37]
	v_mfma_f32_16x16x32_bf16 v[22:25], v[206:209], v[190:193], v[22:25]
	v_mfma_f32_16x16x32_bf16 v[18:21], v[214:217], v[190:193], v[18:21]
	v_mfma_f32_16x16x32_bf16 v[6:9], v[206:209], v[198:201], v[6:9]
	v_mfma_f32_16x16x32_bf16 v[2:5], v[214:217], v[198:201], v[2:5]
	v_mfma_f32_16x16x32_bf16 v[54:57], v[210:213], v[176:179], v[54:57]
	v_mfma_f32_16x16x32_bf16 v[50:53], v[218:221], v[176:179], v[50:53]
	v_mfma_f32_16x16x32_bf16 v[38:41], v[210:213], v[186:189], v[38:41]
	v_mfma_f32_16x16x32_bf16 v[34:37], v[218:221], v[186:189], v[34:37]
	v_mfma_f32_16x16x32_bf16 v[22:25], v[210:213], v[194:197], v[22:25]
	v_mfma_f32_16x16x32_bf16 v[18:21], v[218:221], v[194:197], v[18:21]
	v_mfma_f32_16x16x32_bf16 v[6:9], v[210:213], v[202:205], v[6:9]
	v_mfma_f32_16x16x32_bf16 v[2:5], v[218:221], v[202:205], v[2:5]
	s_add_i32 s24, 32, 0x18000
	s_barrier
	ds_read_b128 v[140:143], v152 offset:32768
	ds_read_b128 v[148:151], v152 offset:33792
	ds_read_b128 v[164:167], v152 offset:34816
	ds_read_b128 v[168:171], v152 offset:35840
	s_add_u32 s2, s2, 0x40000
	s_addc_u32 s3, s3, 0
	s_mov_b32 m0, s21
	ds_read_b128 v[172:175], v147 offset:32768
	ds_read_b128 v[176:179], v147 offset:33792
	ds_read_b128 v[182:185], v147 offset:34816
	ds_read_b128 v[186:189], v147 offset:35840
	ds_read_b128 v[190:193], v147 offset:36864
	ds_read_b128 v[194:197], v147 offset:37888
	ds_read_b128 v[198:201], v147 offset:38912
	ds_read_b128 v[202:205], v147 offset:39936
	global_load_lds_dwordx4 v134, s[2:3]
	s_mov_b32 m0, s22
	s_nop 0
	global_load_lds_dwordx4 v132, s[2:3]
	s_waitcnt lgkmcnt(8)
	s_barrier
	s_waitcnt lgkmcnt(0)
	s_waitcnt lgkmcnt(0)
	v_mfma_f32_16x16x32_bf16 v[126:129], v[140:143], v[172:175], v[126:129]
	v_mfma_f32_16x16x32_bf16 v[122:125], v[164:167], v[172:175], v[122:125]
	v_mfma_f32_16x16x32_bf16 v[110:113], v[140:143], v[182:185], v[110:113]
	v_mfma_f32_16x16x32_bf16 v[106:109], v[164:167], v[182:185], v[106:109]
	v_mfma_f32_16x16x32_bf16 v[94:97], v[140:143], v[190:193], v[94:97]
	v_mfma_f32_16x16x32_bf16 v[90:93], v[164:167], v[190:193], v[90:93]
	v_mfma_f32_16x16x32_bf16 v[78:81], v[140:143], v[198:201], v[78:81]
	v_mfma_f32_16x16x32_bf16 v[74:77], v[164:167], v[198:201], v[74:77]
	v_mfma_f32_16x16x32_bf16 v[126:129], v[148:151], v[176:179], v[126:129]
	v_mfma_f32_16x16x32_bf16 v[122:125], v[168:171], v[176:179], v[122:125]
	v_mfma_f32_16x16x32_bf16 v[110:113], v[148:151], v[186:189], v[110:113]
	v_mfma_f32_16x16x32_bf16 v[106:109], v[168:171], v[186:189], v[106:109]
	v_mfma_f32_16x16x32_bf16 v[94:97], v[148:151], v[194:197], v[94:97]
	v_mfma_f32_16x16x32_bf16 v[90:93], v[168:171], v[194:197], v[90:93]
	v_mfma_f32_16x16x32_bf16 v[78:81], v[148:151], v[202:205], v[78:81]
	v_mfma_f32_16x16x32_bf16 v[74:77], v[168:171], v[202:205], v[74:77]
	s_barrier
	s_add_i32 s38, 32, 0x1c000
	s_add_i32 s2, s24, s7
	s_mov_b32 m0, s2
	ds_read_b128 v[206:209], v152 offset:49152
	ds_read_b128 v[210:213], v152 offset:50176
	ds_read_b128 v[214:217], v152 offset:51200
	ds_read_b128 v[218:221], v152 offset:52224
	s_add_u32 s100, s18, 128
	s_addc_u32 s101, s19, 0
	global_load_lds_dwordx4 v154, s[100:101]
	s_add_i32 m0, s2, 0x2000
	s_nop 0
	global_load_lds_dwordx4 v130, s[100:101]
	s_barrier
	s_waitcnt lgkmcnt(0)
	s_waitcnt lgkmcnt(0)
	v_mfma_f32_16x16x32_bf16 v[118:121], v[206:209], v[172:175], v[118:121]
	v_mfma_f32_16x16x32_bf16 v[114:117], v[214:217], v[172:175], v[114:117]
	v_mfma_f32_16x16x32_bf16 v[102:105], v[206:209], v[182:185], v[102:105]
	v_mfma_f32_16x16x32_bf16 v[98:101], v[214:217], v[182:185], v[98:101]
	v_mfma_f32_16x16x32_bf16 v[86:89], v[206:209], v[190:193], v[86:89]
	v_mfma_f32_16x16x32_bf16 v[82:85], v[214:217], v[190:193], v[82:85]
	v_mfma_f32_16x16x32_bf16 v[70:73], v[206:209], v[198:201], v[70:73]
	v_mfma_f32_16x16x32_bf16 v[66:69], v[214:217], v[198:201], v[66:69]
	v_mfma_f32_16x16x32_bf16 v[118:121], v[210:213], v[176:179], v[118:121]
	v_mfma_f32_16x16x32_bf16 v[114:117], v[218:221], v[176:179], v[114:117]
	v_mfma_f32_16x16x32_bf16 v[102:105], v[210:213], v[186:189], v[102:105]
	v_mfma_f32_16x16x32_bf16 v[98:101], v[218:221], v[186:189], v[98:101]
	v_mfma_f32_16x16x32_bf16 v[86:89], v[210:213], v[194:197], v[86:89]
	v_mfma_f32_16x16x32_bf16 v[82:85], v[218:221], v[194:197], v[82:85]
	v_mfma_f32_16x16x32_bf16 v[70:73], v[210:213], v[202:205], v[70:73]
	v_mfma_f32_16x16x32_bf16 v[66:69], v[218:221], v[202:205], v[66:69]
	s_mov_b32 m0, s23
	s_barrier
	ds_read_b128 v[172:175], v147 offset:49152
	ds_read_b128 v[176:179], v147 offset:50176
	ds_read_b128 v[182:185], v147 offset:51200
	ds_read_b128 v[186:189], v147 offset:52224
	ds_read_b128 v[190:193], v147 offset:53248
	ds_read_b128 v[194:197], v147 offset:54272
	ds_read_b128 v[198:201], v147 offset:55296
	ds_read_b128 v[202:205], v147 offset:56320
	s_add_u32 s98, s98, 128
	s_addc_u32 s99, s99, 0
	global_load_lds_dwordx4 v134, s[98:99]
	s_mov_b32 m0, s28
	s_nop 0
	global_load_lds_dwordx4 v132, s[98:99]
	s_barrier
	s_waitcnt lgkmcnt(0)
	s_waitcnt lgkmcnt(0)
	v_mfma_f32_16x16x32_bf16 v[62:65], v[140:143], v[172:175], v[62:65]
	v_mfma_f32_16x16x32_bf16 v[58:61], v[164:167], v[172:175], v[58:61]
	v_mfma_f32_16x16x32_bf16 v[46:49], v[140:143], v[182:185], v[46:49]
	v_mfma_f32_16x16x32_bf16 v[42:45], v[164:167], v[182:185], v[42:45]
	v_mfma_f32_16x16x32_bf16 v[30:33], v[140:143], v[190:193], v[30:33]
	v_mfma_f32_16x16x32_bf16 v[26:29], v[164:167], v[190:193], v[26:29]
	v_mfma_f32_16x16x32_bf16 v[14:17], v[140:143], v[198:201], v[14:17]
	v_mfma_f32_16x16x32_bf16 v[10:13], v[164:167], v[198:201], v[10:13]
	v_mfma_f32_16x16x32_bf16 v[62:65], v[148:151], v[176:179], v[62:65]
	v_mfma_f32_16x16x32_bf16 v[58:61], v[168:171], v[176:179], v[58:61]
	v_mfma_f32_16x16x32_bf16 v[46:49], v[148:151], v[186:189], v[46:49]
	v_mfma_f32_16x16x32_bf16 v[42:45], v[168:171], v[186:189], v[42:45]
	v_mfma_f32_16x16x32_bf16 v[30:33], v[148:151], v[194:197], v[30:33]
	v_mfma_f32_16x16x32_bf16 v[26:29], v[168:171], v[194:197], v[26:29]
	v_mfma_f32_16x16x32_bf16 v[14:17], v[148:151], v[202:205], v[14:17]
	v_mfma_f32_16x16x32_bf16 v[10:13], v[168:171], v[202:205], v[10:13]
	s_barrier
	s_add_u32 s2, s18, 0x40080
	s_addc_u32 s3, s19, 0
	s_add_i32 s18, s38, s7
	s_mov_b32 m0, s18
	s_nop 0
	global_load_lds_dwordx4 v154, s[2:3]
	s_add_i32 m0, s18, 0x2000
	s_nop 0
	global_load_lds_dwordx4 v130, s[2:3]
	s_waitcnt vmcnt(6)
	s_barrier
	v_mfma_f32_16x16x32_bf16 v[54:57], v[206:209], v[172:175], v[54:57]
	v_mfma_f32_16x16x32_bf16 v[50:53], v[214:217], v[172:175], v[50:53]
	v_mfma_f32_16x16x32_bf16 v[38:41], v[206:209], v[182:185], v[38:41]
	v_mfma_f32_16x16x32_bf16 v[34:37], v[214:217], v[182:185], v[34:37]
	v_mfma_f32_16x16x32_bf16 v[22:25], v[206:209], v[190:193], v[22:25]
	v_mfma_f32_16x16x32_bf16 v[18:21], v[214:217], v[190:193], v[18:21]
	v_mfma_f32_16x16x32_bf16 v[6:9], v[206:209], v[198:201], v[6:9]
	v_mfma_f32_16x16x32_bf16 v[2:5], v[214:217], v[198:201], v[2:5]
	v_mfma_f32_16x16x32_bf16 v[54:57], v[210:213], v[176:179], v[54:57]
	v_mfma_f32_16x16x32_bf16 v[50:53], v[218:221], v[176:179], v[50:53]
	v_mfma_f32_16x16x32_bf16 v[38:41], v[210:213], v[186:189], v[38:41]
	v_mfma_f32_16x16x32_bf16 v[34:37], v[218:221], v[186:189], v[34:37]
	v_mfma_f32_16x16x32_bf16 v[22:25], v[210:213], v[194:197], v[22:25]
	v_mfma_f32_16x16x32_bf16 v[18:21], v[218:221], v[194:197], v[18:21]
	v_mfma_f32_16x16x32_bf16 v[6:9], v[210:213], v[202:205], v[6:9]
	v_mfma_f32_16x16x32_bf16 v[2:5], v[218:221], v[202:205], v[2:5]
	s_add_i32 vcc_hi, vcc_hi, 2
	s_add_u32 s12, s12, 0x100
	s_addc_u32 s13, s13, 0
	s_add_u32 s34, s34, 0x100
	s_addc_u32 s35, s35, 0
	s_cmp_gt_u32 vcc_hi, 13
	s_barrier
	s_cbranch_scc0 .LBB0_935
	v_lshl_add_u32 v142, s36, 8, v144
	v_ashrrev_i32_e32 v143, 31, v142
	v_lshl_or_b32 v140, s37, 8, v146
	v_lshlrev_b64 v[150:151], 11, v[142:143]
	v_ashrrev_i32_e32 v141, 31, v140
	v_lshl_add_u64 v[150:151], s[58:59], 0, v[150:151]
	v_lshl_add_u64 v[164:165], v[140:141], 1, v[150:151]
	v_mov_b64_e32 v[238:239], v[164:165]
	global_load_dwordx4 v[150:153], v[164:165], off
	s_nop 0
	global_load_dwordx4 v[164:167], v[164:165], off offset:256
	v_add_co_u32_e32 v240, vcc, 0x8000, v238
	s_nop 1
	v_addc_co_u32_e32 v241, vcc, 0, v239, vcc
	global_load_dwordx4 v[182:185], v[240:241], off
	global_load_dwordx4 v[186:189], v[240:241], off offset:256
	v_add_co_u32_e32 v240, vcc, 0x10000, v238
	s_nop 1
	v_addc_co_u32_e32 v241, vcc, 0, v239, vcc
	global_load_dwordx4 v[190:193], v[240:241], off
	global_load_dwordx4 v[194:197], v[240:241], off offset:256
	v_add_co_u32_e32 v240, vcc, 0x18000, v238
	s_nop 1
	v_addc_co_u32_e32 v241, vcc, 0, v239, vcc
	global_load_dwordx4 v[198:201], v[240:241], off
	global_load_dwordx4 v[202:205], v[240:241], off offset:256
	v_add_co_u32_e32 v240, vcc, 0x40000, v238
	s_nop 1
	v_addc_co_u32_e32 v241, vcc, 0, v239, vcc
	global_load_dwordx4 v[206:209], v[240:241], off
	global_load_dwordx4 v[210:213], v[240:241], off offset:256
	v_add_co_u32_e32 v240, vcc, 0x48000, v238
	s_nop 1
	v_addc_co_u32_e32 v241, vcc, 0, v239, vcc
	global_load_dwordx4 v[214:217], v[240:241], off
	global_load_dwordx4 v[218:221], v[240:241], off offset:256
	v_add_co_u32_e32 v240, vcc, 0x50000, v238
	s_nop 1
	v_addc_co_u32_e32 v241, vcc, 0, v239, vcc
	global_load_dwordx4 v[222:225], v[240:241], off
	global_load_dwordx4 v[226:229], v[240:241], off offset:256
	v_add_co_u32_e32 v240, vcc, 0x58000, v238
	s_nop 1
	v_addc_co_u32_e32 v241, vcc, 0, v239, vcc
	global_load_dwordx4 v[230:233], v[240:241], off
	global_load_dwordx4 v[234:237], v[240:241], off offset:256
	v_lshlrev_b32_e32 v148, 1, v140
	s_waitcnt vmcnt(14)
	v_lshlrev_b32_e32 v149, 16, v150
	v_lshlrev_b32_e32 v171, 16, v164
	v_and_b32_e32 v164, 0xffff0000, v164
	v_and_b32_e32 v150, 0xffff0000, v150
	v_lshlrev_b32_e32 v168, 16, v151
	v_and_b32_e32 v151, 0xffff0000, v151
	v_lshlrev_b32_e32 v173, 16, v166
	v_and_b32_e32 v166, 0xffff0000, v166
	v_lshlrev_b32_e32 v174, 16, v167
	v_and_b32_e32 v167, 0xffff0000, v167
	v_add_f32_e32 v118, v118, v171
	v_add_f32_e32 v119, v119, v164
	v_lshlrev_b32_e32 v172, 16, v165
	v_add_f32_e32 v126, v126, v149
	v_add_f32_e32 v149, v114, v173
	v_add_f32_e32 v114, v127, v150
	v_add_f32_e32 v127, v115, v166
	v_add_f32_e32 v115, v128, v168
	v_add_f32_e32 v128, v116, v174
	v_add_f32_e32 v116, v129, v151
	v_add_f32_e32 v129, v117, v167
	v_mul_f32_e32 v117, v118, v118
	v_mul_f32_e32 v150, v119, v119
	v_add_f32_e32 v120, v120, v172
	v_fmac_f32_e32 v117, v126, v126
	v_fmac_f32_e32 v150, v114, v114
	v_and_b32_e32 v165, 0xffff0000, v165
	v_add_f32_e32 v117, v117, v150
	v_mul_f32_e32 v150, v120, v120
	v_add_f32_e32 v121, v121, v165
	v_fmac_f32_e32 v150, v115, v115
	v_add_f32_e32 v117, v150, v117
	v_mul_f32_e32 v150, v121, v121
	v_lshlrev_b32_e32 v169, 16, v152
	v_fmac_f32_e32 v150, v116, v116
	v_add_f32_e32 v122, v122, v169
	v_add_f32_e32 v117, v150, v117
	v_mul_f32_e32 v150, v149, v149
	v_and_b32_e32 v152, 0xffff0000, v152
	v_fmac_f32_e32 v150, v122, v122
	v_add_f32_e32 v123, v123, v152
	v_add_f32_e32 v117, v150, v117
	v_mul_f32_e32 v150, v127, v127
	v_lshlrev_b32_e32 v170, 16, v153
	v_fmac_f32_e32 v150, v123, v123
	v_add_f32_e32 v124, v124, v170
	v_add_f32_e32 v117, v150, v117
	v_mul_f32_e32 v150, v128, v128
	v_and_b32_e32 v153, 0xffff0000, v153
	v_fmac_f32_e32 v150, v124, v124
	v_add_f32_e32 v125, v125, v153
	v_add_f32_e32 v117, v150, v117
	v_mul_f32_e32 v150, v129, v129
	v_fmac_f32_e32 v150, v125, v125
	v_lshl_add_u32 v151, v142, 11, v148
	v_cvt_pk_bf16_f32 v114, v126, v114
	v_cvt_pk_bf16_f32 v115, v115, v116
	v_add_f32_e32 v150, v150, v117
	v_cvt_pk_bf16_f32 v116, v122, v123
	v_cvt_pk_bf16_f32 v117, v124, v125
	v_and_b32_e32 v245, 3, v0
	v_bfe_u32 v246, v0, 2, 4
	v_lshl_add_u32 v247, v245, 4, v246
	v_lshlrev_b32_e32 v247, 2, v247
	v_and_b32_e32 v252, 15, v0
	v_sub_u32_e32 v246, v246, v252
	v_lshlrev_b32_e32 v246, 11, v246
	v_bfe_u32 v252, v0, 4, 2
	v_sub_u32_e32 v245, v245, v252
	v_lshl_add_u32 v246, v245, 4, v246
	v_mov_b32_e32 v245, v247
	v_add_u32_e32 v247, v246, v151
	ds_bpermute_b32 v252, v245, v114
	ds_bpermute_b32 v253, v245, v115
	ds_bpermute_b32 v254, v245, v116
	ds_bpermute_b32 v255, v245, v117
	s_nop 1
	v_cvt_pk_bf16_f32 v114, v118, v119
	v_cvt_pk_bf16_f32 v115, v120, v121
	v_cvt_pk_bf16_f32 v116, v149, v127
	v_cvt_pk_bf16_f32 v117, v128, v129
	s_waitcnt lgkmcnt(0)
	buffer_store_dwordx4 v[252:255], v247, s[64:67], 0 offen sc1
	v_add_u32_e32 v247, v246, v151
	ds_bpermute_b32 v252, v245, v114
	ds_bpermute_b32 v253, v245, v115
	ds_bpermute_b32 v254, v245, v116
	ds_bpermute_b32 v255, v245, v117
	s_nop 1
	v_and_b32_e32 v115, 64, v181
	v_xor_b32_e32 v114, 16, v181
	v_add_u32_e32 v115, 64, v115
	v_cmp_lt_i32_e32 vcc, v114, v115
	v_xor_b32_e32 v117, 32, v181
	s_nop 0
	v_cndmask_b32_e32 v114, v181, v114, vcc
	v_lshlrev_b32_e32 v116, 2, v114
	v_mov_b32_e32 v114, v150
	s_nop 1
	v_permlane16_swap_b32 v114, v150
	v_cmp_lt_i32_e32 vcc, v117, v115
	s_waitcnt lgkmcnt(0)
	v_add_f32_e32 v114, v150, v114
	v_cndmask_b32_e32 v115, v181, v117, vcc
	v_lshlrev_b32_e32 v117, 2, v115
	v_mov_b32_e32 v115, v114
	s_nop 1
	v_permlane32_swap_b32 v115, v114
	s_and_saveexec_b64 s[2:3], s[40:41]
	s_cbranch_execz .LBB0_938
	v_lshl_add_u64 v[118:119], v[142:143], 2, s[0:1]
	s_waitcnt lgkmcnt(0)
	v_add_f32_e32 v114, v114, v115
	global_atomic_add_f32 v[118:119], v114, off
.LBB0_938:
	s_or_b64 exec, exec, s[2:3]
	v_or_b32_e32 v114, 16, v142
	s_waitcnt lgkmcnt(0)
	v_ashrrev_i32_e32 v115, 31, v114
	v_lshlrev_b64 v[118:119], 11, v[114:115]
	v_lshl_add_u64 v[118:119], s[58:59], 0, v[118:119]
	v_lshl_add_u64 v[122:123], v[140:141], 1, v[118:119]
	s_waitcnt vmcnt(15)
	v_mov_b64_e32 v[118:119], v[182:183]
	v_mov_b64_e32 v[120:121], v[184:185]
	s_nop 0
	v_mov_b64_e32 v[122:123], v[186:187]
	v_mov_b64_e32 v[124:125], v[188:189]
	v_lshlrev_b32_e32 v126, 16, v118
	v_and_b32_e32 v118, 0xffff0000, v118
	v_lshlrev_b32_e32 v143, 16, v122
	v_and_b32_e32 v122, 0xffff0000, v122
	v_lshlrev_b32_e32 v127, 16, v119
	v_lshlrev_b32_e32 v128, 16, v120
	v_lshlrev_b32_e32 v150, 16, v124
	v_lshlrev_b32_e32 v151, 16, v125
	v_add_f32_e32 v110, v110, v126
	v_add_f32_e32 v126, v102, v143
	v_add_f32_e32 v102, v111, v118
	v_add_f32_e32 v111, v103, v122
	v_lshlrev_b32_e32 v149, 16, v123
	v_add_f32_e32 v106, v106, v128
	v_add_f32_e32 v128, v98, v150
	v_add_f32_e32 v103, v112, v127
	v_add_f32_e32 v112, v100, v151
	v_mul_f32_e32 v98, v126, v126
	v_mul_f32_e32 v100, v111, v111
	v_add_f32_e32 v104, v104, v149
	v_fmac_f32_e32 v98, v110, v110
	v_fmac_f32_e32 v100, v102, v102
	v_and_b32_e32 v123, 0xffff0000, v123
	v_add_f32_e32 v98, v98, v100
	v_mul_f32_e32 v100, v104, v104
	v_and_b32_e32 v119, 0xffff0000, v119
	v_add_f32_e32 v105, v105, v123
	v_fmac_f32_e32 v100, v103, v103
	v_add_f32_e32 v113, v113, v119
	v_add_f32_e32 v98, v100, v98
	v_mul_f32_e32 v100, v105, v105
	v_fmac_f32_e32 v100, v113, v113
	v_and_b32_e32 v124, 0xffff0000, v124
	v_add_f32_e32 v98, v100, v98
	v_mul_f32_e32 v100, v128, v128
	v_and_b32_e32 v120, 0xffff0000, v120
	v_add_f32_e32 v99, v99, v124
	v_fmac_f32_e32 v100, v106, v106
	v_add_f32_e32 v107, v107, v120
	v_add_f32_e32 v98, v100, v98
	v_mul_f32_e32 v100, v99, v99
	v_lshlrev_b32_e32 v129, 16, v121
	v_fmac_f32_e32 v100, v107, v107
	v_and_b32_e32 v125, 0xffff0000, v125
	v_add_f32_e32 v108, v108, v129
	v_add_f32_e32 v98, v100, v98
	v_mul_f32_e32 v100, v112, v112
	v_and_b32_e32 v121, 0xffff0000, v121
	v_add_f32_e32 v118, v101, v125
	v_fmac_f32_e32 v100, v108, v108
	v_add_f32_e32 v109, v109, v121
	v_add_f32_e32 v98, v100, v98
	v_mul_f32_e32 v100, v118, v118
	v_fmac_f32_e32 v100, v109, v109
	v_add_f32_e32 v98, v100, v98
	v_lshl_add_u32 v119, v114, 11, v148
	v_cvt_pk_bf16_f32 v100, v110, v102
	v_cvt_pk_bf16_f32 v101, v103, v113
	v_cvt_pk_bf16_f32 v102, v106, v107
	v_cvt_pk_bf16_f32 v103, v108, v109
	s_waitcnt lgkmcnt(0)
	buffer_store_dwordx4 v[252:255], v247, s[64:67], 0 offen offset:256 sc1
	v_add_u32_e32 v247, v246, v119
	ds_bpermute_b32 v252, v245, v100
	ds_bpermute_b32 v253, v245, v101
	ds_bpermute_b32 v254, v245, v102
	ds_bpermute_b32 v255, v245, v103
	s_nop 1
	v_cvt_pk_bf16_f32 v100, v126, v111
	v_cvt_pk_bf16_f32 v101, v104, v105
	v_cvt_pk_bf16_f32 v102, v128, v99
	v_mov_b32_e32 v99, v98
	s_nop 1
	v_permlane16_swap_b32 v99, v98
	v_cvt_pk_bf16_f32 v103, v112, v118
	s_waitcnt lgkmcnt(0)
	buffer_store_dwordx4 v[252:255], v247, s[64:67], 0 offen sc1
	v_add_u32_e32 v247, v246, v119
	ds_bpermute_b32 v252, v245, v100
	ds_bpermute_b32 v253, v245, v101
	ds_bpermute_b32 v254, v245, v102
	ds_bpermute_b32 v255, v245, v103
	s_waitcnt lgkmcnt(0)
	v_add_f32_e32 v98, v98, v99
	v_mov_b32_e32 v99, v98
	s_nop 1
	v_permlane32_swap_b32 v99, v98
	s_and_saveexec_b64 s[2:3], s[40:41]
	s_cbranch_execz .LBB0_940
	v_lshl_add_u64 v[100:101], v[114:115], 2, s[0:1]
	s_waitcnt lgkmcnt(0)
	v_add_f32_e32 v98, v98, v99
	global_atomic_add_f32 v[100:101], v98, off
.LBB0_940:
	s_or_b64 exec, exec, s[2:3]
	v_or_b32_e32 v98, 32, v142
	s_waitcnt lgkmcnt(0)
	v_ashrrev_i32_e32 v99, 31, v98
	v_lshlrev_b64 v[100:101], 11, v[98:99]
	v_lshl_add_u64 v[100:101], s[58:59], 0, v[100:101]
	v_lshl_add_u64 v[104:105], v[140:141], 1, v[100:101]
	s_waitcnt vmcnt(16)
	v_mov_b64_e32 v[100:101], v[190:191]
	v_mov_b64_e32 v[102:103], v[192:193]
	s_nop 0
	v_mov_b64_e32 v[104:105], v[194:195]
	v_mov_b64_e32 v[106:107], v[196:197]
	v_lshlrev_b32_e32 v108, 16, v100
	v_and_b32_e32 v100, 0xffff0000, v100
	v_lshlrev_b32_e32 v112, 16, v104
	v_and_b32_e32 v104, 0xffff0000, v104
	v_lshlrev_b32_e32 v109, 16, v101
	v_lshlrev_b32_e32 v110, 16, v102
	v_lshlrev_b32_e32 v114, 16, v106
	v_lshlrev_b32_e32 v115, 16, v107
	v_add_f32_e32 v94, v94, v108
	v_add_f32_e32 v108, v86, v112
	v_add_f32_e32 v86, v95, v100
	v_add_f32_e32 v95, v87, v104
	v_lshlrev_b32_e32 v113, 16, v105
	v_add_f32_e32 v90, v90, v110
	v_add_f32_e32 v110, v82, v114
	v_add_f32_e32 v87, v96, v109
	v_add_f32_e32 v96, v84, v115
	v_mul_f32_e32 v82, v108, v108
	v_mul_f32_e32 v84, v95, v95
	v_add_f32_e32 v88, v88, v113
	v_fmac_f32_e32 v82, v94, v94
	v_fmac_f32_e32 v84, v86, v86
	v_and_b32_e32 v105, 0xffff0000, v105
	v_add_f32_e32 v82, v82, v84
	v_mul_f32_e32 v84, v88, v88
	v_and_b32_e32 v101, 0xffff0000, v101
	v_add_f32_e32 v89, v89, v105
	v_fmac_f32_e32 v84, v87, v87
	v_add_f32_e32 v97, v97, v101
	v_add_f32_e32 v82, v84, v82
	v_mul_f32_e32 v84, v89, v89
	v_fmac_f32_e32 v84, v97, v97
	v_and_b32_e32 v106, 0xffff0000, v106
	v_add_f32_e32 v82, v84, v82
	v_mul_f32_e32 v84, v110, v110
	v_and_b32_e32 v102, 0xffff0000, v102
	v_add_f32_e32 v83, v83, v106
	v_fmac_f32_e32 v84, v90, v90
	v_add_f32_e32 v91, v91, v102
	v_add_f32_e32 v82, v84, v82
	v_mul_f32_e32 v84, v83, v83
	v_lshlrev_b32_e32 v111, 16, v103
	v_fmac_f32_e32 v84, v91, v91
	v_and_b32_e32 v107, 0xffff0000, v107
	v_add_f32_e32 v92, v92, v111
	v_add_f32_e32 v82, v84, v82
	v_mul_f32_e32 v84, v96, v96
	v_and_b32_e32 v103, 0xffff0000, v103
	v_add_f32_e32 v100, v85, v107
	v_fmac_f32_e32 v84, v92, v92
	v_add_f32_e32 v93, v93, v103
	v_add_f32_e32 v82, v84, v82
	v_mul_f32_e32 v84, v100, v100
	v_fmac_f32_e32 v84, v93, v93
	v_add_f32_e32 v82, v84, v82
	v_lshl_add_u32 v101, v98, 11, v148
	v_cvt_pk_bf16_f32 v84, v94, v86
	v_cvt_pk_bf16_f32 v85, v87, v97
	v_cvt_pk_bf16_f32 v86, v90, v91
	v_cvt_pk_bf16_f32 v87, v92, v93
	s_waitcnt lgkmcnt(0)
	buffer_store_dwordx4 v[252:255], v247, s[64:67], 0 offen offset:256 sc1
	v_add_u32_e32 v247, v246, v101
	ds_bpermute_b32 v252, v245, v84
	ds_bpermute_b32 v253, v245, v85
	ds_bpermute_b32 v254, v245, v86
	ds_bpermute_b32 v255, v245, v87
	s_nop 1
	v_cvt_pk_bf16_f32 v84, v108, v95
	v_cvt_pk_bf16_f32 v85, v88, v89
	v_cvt_pk_bf16_f32 v86, v110, v83
	v_mov_b32_e32 v83, v82
	s_nop 1
	v_permlane16_swap_b32 v83, v82
	v_cvt_pk_bf16_f32 v87, v96, v100
	s_waitcnt lgkmcnt(0)
	buffer_store_dwordx4 v[252:255], v247, s[64:67], 0 offen sc1
	v_add_u32_e32 v247, v246, v101
	ds_bpermute_b32 v252, v245, v84
	ds_bpermute_b32 v253, v245, v85
	ds_bpermute_b32 v254, v245, v86
	ds_bpermute_b32 v255, v245, v87
	s_waitcnt lgkmcnt(0)
	v_add_f32_e32 v82, v82, v83
	v_mov_b32_e32 v83, v82
	s_nop 1
	v_permlane32_swap_b32 v83, v82
	s_and_saveexec_b64 s[2:3], s[40:41]
	s_cbranch_execz .LBB0_942
	v_lshl_add_u64 v[84:85], v[98:99], 2, s[0:1]
	s_waitcnt lgkmcnt(0)
	v_add_f32_e32 v82, v82, v83
	global_atomic_add_f32 v[84:85], v82, off
.LBB0_942:
	s_or_b64 exec, exec, s[2:3]
	v_or_b32_e32 v82, 48, v142
	s_waitcnt lgkmcnt(0)
	v_ashrrev_i32_e32 v83, 31, v82
	v_lshlrev_b64 v[84:85], 11, v[82:83]
	v_lshl_add_u64 v[84:85], s[58:59], 0, v[84:85]
	v_lshl_add_u64 v[88:89], v[140:141], 1, v[84:85]
	s_waitcnt vmcnt(17)
	v_mov_b64_e32 v[84:85], v[198:199]
	v_mov_b64_e32 v[86:87], v[200:201]
	s_nop 0
	v_mov_b64_e32 v[88:89], v[202:203]
	v_mov_b64_e32 v[90:91], v[204:205]
	v_lshlrev_b32_e32 v92, 16, v84
	v_and_b32_e32 v84, 0xffff0000, v84
	v_lshlrev_b32_e32 v96, 16, v88
	v_and_b32_e32 v88, 0xffff0000, v88
	v_lshlrev_b32_e32 v93, 16, v85
	v_lshlrev_b32_e32 v94, 16, v86
	v_lshlrev_b32_e32 v98, 16, v90
	v_lshlrev_b32_e32 v99, 16, v91
	v_add_f32_e32 v78, v78, v92
	v_add_f32_e32 v92, v70, v96
	v_add_f32_e32 v70, v79, v84
	v_add_f32_e32 v79, v71, v88
	v_lshlrev_b32_e32 v97, 16, v89
	v_add_f32_e32 v74, v74, v94
	v_add_f32_e32 v94, v66, v98
	v_add_f32_e32 v71, v80, v93
	v_add_f32_e32 v80, v68, v99
	v_mul_f32_e32 v66, v92, v92
	v_mul_f32_e32 v68, v79, v79
	v_add_f32_e32 v72, v72, v97
	v_fmac_f32_e32 v66, v78, v78
	v_fmac_f32_e32 v68, v70, v70
	v_and_b32_e32 v89, 0xffff0000, v89
	v_add_f32_e32 v66, v66, v68
	v_mul_f32_e32 v68, v72, v72
	v_and_b32_e32 v85, 0xffff0000, v85
	v_add_f32_e32 v73, v73, v89
	v_fmac_f32_e32 v68, v71, v71
	v_add_f32_e32 v81, v81, v85
	v_add_f32_e32 v66, v68, v66
	v_mul_f32_e32 v68, v73, v73
	v_fmac_f32_e32 v68, v81, v81
	v_and_b32_e32 v90, 0xffff0000, v90
	v_add_f32_e32 v66, v68, v66
	v_mul_f32_e32 v68, v94, v94
	v_and_b32_e32 v86, 0xffff0000, v86
	v_add_f32_e32 v67, v67, v90
	v_fmac_f32_e32 v68, v74, v74
	v_add_f32_e32 v75, v75, v86
	v_add_f32_e32 v66, v68, v66
	v_mul_f32_e32 v68, v67, v67
	v_lshlrev_b32_e32 v95, 16, v87
	v_fmac_f32_e32 v68, v75, v75
	v_and_b32_e32 v91, 0xffff0000, v91
	v_add_f32_e32 v76, v76, v95
	v_add_f32_e32 v66, v68, v66
	v_mul_f32_e32 v68, v80, v80
	v_and_b32_e32 v87, 0xffff0000, v87
	v_add_f32_e32 v84, v69, v91
	v_fmac_f32_e32 v68, v76, v76
	v_add_f32_e32 v77, v77, v87
	v_add_f32_e32 v66, v68, v66
	v_mul_f32_e32 v68, v84, v84
	v_fmac_f32_e32 v68, v77, v77
	v_add_f32_e32 v66, v68, v66
	v_lshl_add_u32 v85, v82, 11, v148
	v_cvt_pk_bf16_f32 v68, v78, v70
	v_cvt_pk_bf16_f32 v69, v71, v81
	v_cvt_pk_bf16_f32 v70, v74, v75
	v_cvt_pk_bf16_f32 v71, v76, v77
	s_waitcnt lgkmcnt(0)
	buffer_store_dwordx4 v[252:255], v247, s[64:67], 0 offen offset:256 sc1
	v_add_u32_e32 v247, v246, v85
	ds_bpermute_b32 v252, v245, v68
	ds_bpermute_b32 v253, v245, v69
	ds_bpermute_b32 v254, v245, v70
	ds_bpermute_b32 v255, v245, v71
	s_nop 1
	v_cvt_pk_bf16_f32 v68, v92, v79
	v_cvt_pk_bf16_f32 v69, v72, v73
	v_cvt_pk_bf16_f32 v70, v94, v67
	v_mov_b32_e32 v67, v66
	s_nop 1
	v_permlane16_swap_b32 v67, v66
	v_cvt_pk_bf16_f32 v71, v80, v84
	s_waitcnt lgkmcnt(0)
	buffer_store_dwordx4 v[252:255], v247, s[64:67], 0 offen sc1
	v_add_u32_e32 v247, v246, v85
	ds_bpermute_b32 v252, v245, v68
	ds_bpermute_b32 v253, v245, v69
	ds_bpermute_b32 v254, v245, v70
	ds_bpermute_b32 v255, v245, v71
	s_waitcnt lgkmcnt(0)
	v_add_f32_e32 v66, v66, v67
	v_mov_b32_e32 v67, v66
	s_nop 1
	v_permlane32_swap_b32 v67, v66
	s_and_saveexec_b64 s[2:3], s[40:41]
	v_readlane_b32 s24, v244, 11
	v_readlane_b32 s18, v242, 47
	v_readlane_b32 s19, v242, 48
	s_cbranch_execz .LBB0_944
	v_lshl_add_u64 v[68:69], v[82:83], 2, s[0:1]
	s_waitcnt lgkmcnt(0)
	v_add_f32_e32 v66, v66, v67
	global_atomic_add_f32 v[68:69], v66, off
.LBB0_944:
	s_or_b64 exec, exec, s[2:3]
	v_add_u32_e32 v66, 0x80, v142
	s_waitcnt lgkmcnt(0)
	v_ashrrev_i32_e32 v67, 31, v66
	v_lshlrev_b64 v[68:69], 11, v[66:67]
	v_lshl_add_u64 v[68:69], s[58:59], 0, v[68:69]
	v_lshl_add_u64 v[72:73], v[140:141], 1, v[68:69]
	s_waitcnt vmcnt(18)
	v_mov_b64_e32 v[68:69], v[206:207]
	v_mov_b64_e32 v[70:71], v[208:209]
	s_nop 0
	v_mov_b64_e32 v[72:73], v[210:211]
	v_mov_b64_e32 v[74:75], v[212:213]
	v_lshlrev_b32_e32 v76, 16, v68
	v_and_b32_e32 v68, 0xffff0000, v68
	v_lshlrev_b32_e32 v80, 16, v72
	v_and_b32_e32 v72, 0xffff0000, v72
	v_lshlrev_b32_e32 v77, 16, v69
	v_lshlrev_b32_e32 v78, 16, v70
	v_lshlrev_b32_e32 v82, 16, v74
	v_lshlrev_b32_e32 v83, 16, v75
	v_add_f32_e32 v62, v62, v76
	v_add_f32_e32 v76, v54, v80
	v_add_f32_e32 v54, v63, v68
	v_add_f32_e32 v63, v55, v72
	v_lshlrev_b32_e32 v81, 16, v73
	v_add_f32_e32 v58, v58, v78
	v_add_f32_e32 v78, v50, v82
	v_add_f32_e32 v55, v64, v77
	v_add_f32_e32 v64, v52, v83
	v_mul_f32_e32 v50, v76, v76
	v_mul_f32_e32 v52, v63, v63
	v_add_f32_e32 v56, v56, v81
	v_fmac_f32_e32 v50, v62, v62
	v_fmac_f32_e32 v52, v54, v54
	v_and_b32_e32 v73, 0xffff0000, v73
	v_add_f32_e32 v50, v50, v52
	v_mul_f32_e32 v52, v56, v56
	v_and_b32_e32 v69, 0xffff0000, v69
	v_add_f32_e32 v57, v57, v73
	v_fmac_f32_e32 v52, v55, v55
	v_add_f32_e32 v65, v65, v69
	v_add_f32_e32 v50, v52, v50
	v_mul_f32_e32 v52, v57, v57
	v_fmac_f32_e32 v52, v65, v65
	v_and_b32_e32 v74, 0xffff0000, v74
	v_add_f32_e32 v50, v52, v50
	v_mul_f32_e32 v52, v78, v78
	v_and_b32_e32 v70, 0xffff0000, v70
	v_add_f32_e32 v51, v51, v74
	v_fmac_f32_e32 v52, v58, v58
	v_add_f32_e32 v59, v59, v70
	v_add_f32_e32 v50, v52, v50
	v_mul_f32_e32 v52, v51, v51
	v_lshlrev_b32_e32 v79, 16, v71
	v_fmac_f32_e32 v52, v59, v59
	v_and_b32_e32 v75, 0xffff0000, v75
	v_add_f32_e32 v60, v60, v79
	v_add_f32_e32 v50, v52, v50
	v_mul_f32_e32 v52, v64, v64
	v_and_b32_e32 v71, 0xffff0000, v71
	v_add_f32_e32 v68, v53, v75
	v_fmac_f32_e32 v52, v60, v60
	v_add_f32_e32 v61, v61, v71
	v_add_f32_e32 v50, v52, v50
	v_mul_f32_e32 v52, v68, v68
	v_fmac_f32_e32 v52, v61, v61
	v_add_f32_e32 v50, v52, v50
	v_lshl_add_u32 v69, v66, 11, v148
	v_cvt_pk_bf16_f32 v52, v62, v54
	v_cvt_pk_bf16_f32 v53, v55, v65
	v_cvt_pk_bf16_f32 v54, v58, v59
	v_cvt_pk_bf16_f32 v55, v60, v61
	s_waitcnt lgkmcnt(0)
	buffer_store_dwordx4 v[252:255], v247, s[64:67], 0 offen offset:256 sc1
	v_add_u32_e32 v247, v246, v69
	ds_bpermute_b32 v252, v245, v52
	ds_bpermute_b32 v253, v245, v53
	ds_bpermute_b32 v254, v245, v54
	ds_bpermute_b32 v255, v245, v55
	s_nop 1
	v_cvt_pk_bf16_f32 v52, v76, v63
	v_cvt_pk_bf16_f32 v53, v56, v57
	v_cvt_pk_bf16_f32 v54, v78, v51
	v_mov_b32_e32 v51, v50
	s_nop 1
	v_permlane16_swap_b32 v51, v50
	v_cvt_pk_bf16_f32 v55, v64, v68
	s_waitcnt lgkmcnt(0)
	buffer_store_dwordx4 v[252:255], v247, s[64:67], 0 offen sc1
	v_add_u32_e32 v247, v246, v69
	ds_bpermute_b32 v252, v245, v52
	ds_bpermute_b32 v253, v245, v53
	ds_bpermute_b32 v254, v245, v54
	ds_bpermute_b32 v255, v245, v55
	s_waitcnt lgkmcnt(0)
	v_add_f32_e32 v50, v50, v51
	v_mov_b32_e32 v51, v50
	s_nop 1
	v_permlane32_swap_b32 v51, v50
	s_and_saveexec_b64 s[2:3], s[40:41]
	s_cbranch_execz .LBB0_946
	v_lshl_add_u64 v[52:53], v[66:67], 2, s[0:1]
	s_waitcnt lgkmcnt(0)
	v_add_f32_e32 v50, v50, v51
	global_atomic_add_f32 v[52:53], v50, off
.LBB0_946:
	s_or_b64 exec, exec, s[2:3]
	v_add_u32_e32 v50, 0x90, v142
	s_waitcnt lgkmcnt(0)
	v_ashrrev_i32_e32 v51, 31, v50
	v_lshlrev_b64 v[52:53], 11, v[50:51]
	v_lshl_add_u64 v[52:53], s[58:59], 0, v[52:53]
	v_lshl_add_u64 v[56:57], v[140:141], 1, v[52:53]
	s_waitcnt vmcnt(19)
	v_mov_b64_e32 v[52:53], v[214:215]
	v_mov_b64_e32 v[54:55], v[216:217]
	s_nop 0
	v_mov_b64_e32 v[56:57], v[218:219]
	v_mov_b64_e32 v[58:59], v[220:221]
	v_lshlrev_b32_e32 v60, 16, v52
	v_and_b32_e32 v52, 0xffff0000, v52
	v_lshlrev_b32_e32 v64, 16, v56
	v_and_b32_e32 v56, 0xffff0000, v56
	v_lshlrev_b32_e32 v61, 16, v53
	v_lshlrev_b32_e32 v62, 16, v54
	v_lshlrev_b32_e32 v66, 16, v58
	v_lshlrev_b32_e32 v67, 16, v59
	v_add_f32_e32 v46, v46, v60
	v_add_f32_e32 v60, v38, v64
	v_add_f32_e32 v38, v47, v52
	v_add_f32_e32 v47, v39, v56
	v_lshlrev_b32_e32 v65, 16, v57
	v_add_f32_e32 v42, v42, v62
	v_add_f32_e32 v62, v34, v66
	v_add_f32_e32 v39, v48, v61
	v_add_f32_e32 v48, v36, v67
	v_mul_f32_e32 v34, v60, v60
	v_mul_f32_e32 v36, v47, v47
	v_add_f32_e32 v40, v40, v65
	v_fmac_f32_e32 v34, v46, v46
	v_fmac_f32_e32 v36, v38, v38
	v_and_b32_e32 v57, 0xffff0000, v57
	v_add_f32_e32 v34, v34, v36
	v_mul_f32_e32 v36, v40, v40
	v_and_b32_e32 v53, 0xffff0000, v53
	v_add_f32_e32 v41, v41, v57
	v_fmac_f32_e32 v36, v39, v39
	v_add_f32_e32 v49, v49, v53
	v_add_f32_e32 v34, v36, v34
	v_mul_f32_e32 v36, v41, v41
	v_fmac_f32_e32 v36, v49, v49
	v_and_b32_e32 v58, 0xffff0000, v58
	v_add_f32_e32 v34, v36, v34
	v_mul_f32_e32 v36, v62, v62
	v_and_b32_e32 v54, 0xffff0000, v54
	v_add_f32_e32 v35, v35, v58
	v_fmac_f32_e32 v36, v42, v42
	v_add_f32_e32 v43, v43, v54
	v_add_f32_e32 v34, v36, v34
	v_mul_f32_e32 v36, v35, v35
	v_lshlrev_b32_e32 v63, 16, v55
	v_fmac_f32_e32 v36, v43, v43
	v_and_b32_e32 v59, 0xffff0000, v59
	v_add_f32_e32 v44, v44, v63
	v_add_f32_e32 v34, v36, v34
	v_mul_f32_e32 v36, v48, v48
	v_and_b32_e32 v55, 0xffff0000, v55
	v_add_f32_e32 v52, v37, v59
	v_fmac_f32_e32 v36, v44, v44
	v_add_f32_e32 v45, v45, v55
	v_add_f32_e32 v34, v36, v34
	v_mul_f32_e32 v36, v52, v52
	v_fmac_f32_e32 v36, v45, v45
	v_add_f32_e32 v34, v36, v34
	v_lshl_add_u32 v53, v50, 11, v148
	v_cvt_pk_bf16_f32 v36, v46, v38
	v_cvt_pk_bf16_f32 v37, v39, v49
	v_cvt_pk_bf16_f32 v38, v42, v43
	v_cvt_pk_bf16_f32 v39, v44, v45
	s_waitcnt lgkmcnt(0)
	buffer_store_dwordx4 v[252:255], v247, s[64:67], 0 offen offset:256 sc1
	v_add_u32_e32 v247, v246, v53
	ds_bpermute_b32 v252, v245, v36
	ds_bpermute_b32 v253, v245, v37
	ds_bpermute_b32 v254, v245, v38
	ds_bpermute_b32 v255, v245, v39
	s_nop 1
	v_cvt_pk_bf16_f32 v36, v60, v47
	v_cvt_pk_bf16_f32 v37, v40, v41
	v_cvt_pk_bf16_f32 v38, v62, v35
	v_mov_b32_e32 v35, v34
	s_nop 1
	v_permlane16_swap_b32 v35, v34
	v_cvt_pk_bf16_f32 v39, v48, v52
	s_waitcnt lgkmcnt(0)
	buffer_store_dwordx4 v[252:255], v247, s[64:67], 0 offen sc1
	v_add_u32_e32 v247, v246, v53
	ds_bpermute_b32 v252, v245, v36
	ds_bpermute_b32 v253, v245, v37
	ds_bpermute_b32 v254, v245, v38
	ds_bpermute_b32 v255, v245, v39
	s_waitcnt lgkmcnt(0)
	v_add_f32_e32 v34, v34, v35
	v_mov_b32_e32 v35, v34
	s_nop 1
	v_permlane32_swap_b32 v35, v34
	s_and_saveexec_b64 s[2:3], s[40:41]
	s_cbranch_execz .LBB0_948
	v_lshl_add_u64 v[36:37], v[50:51], 2, s[0:1]
	s_waitcnt lgkmcnt(0)
	v_add_f32_e32 v34, v34, v35
	global_atomic_add_f32 v[36:37], v34, off
.LBB0_948:
	s_or_b64 exec, exec, s[2:3]
	v_add_u32_e32 v34, 0xa0, v142
	s_waitcnt lgkmcnt(0)
	v_ashrrev_i32_e32 v35, 31, v34
	v_lshlrev_b64 v[36:37], 11, v[34:35]
	v_lshl_add_u64 v[36:37], s[58:59], 0, v[36:37]
	v_lshl_add_u64 v[40:41], v[140:141], 1, v[36:37]
	s_waitcnt vmcnt(20)
	v_mov_b64_e32 v[36:37], v[222:223]
	v_mov_b64_e32 v[38:39], v[224:225]
	s_nop 0
	v_mov_b64_e32 v[40:41], v[226:227]
	v_mov_b64_e32 v[42:43], v[228:229]
	v_lshlrev_b32_e32 v44, 16, v36
	v_and_b32_e32 v36, 0xffff0000, v36
	v_lshlrev_b32_e32 v48, 16, v40
	v_and_b32_e32 v40, 0xffff0000, v40
	v_lshlrev_b32_e32 v45, 16, v37
	v_lshlrev_b32_e32 v46, 16, v38
	v_lshlrev_b32_e32 v50, 16, v42
	v_lshlrev_b32_e32 v51, 16, v43
	v_add_f32_e32 v30, v30, v44
	v_add_f32_e32 v44, v22, v48
	v_add_f32_e32 v22, v31, v36
	v_add_f32_e32 v31, v23, v40
	v_lshlrev_b32_e32 v49, 16, v41
	v_add_f32_e32 v26, v26, v46
	v_add_f32_e32 v46, v18, v50
	v_add_f32_e32 v23, v32, v45
	v_add_f32_e32 v32, v20, v51
	v_mul_f32_e32 v18, v44, v44
	v_mul_f32_e32 v20, v31, v31
	v_add_f32_e32 v24, v24, v49
	v_fmac_f32_e32 v18, v30, v30
	v_fmac_f32_e32 v20, v22, v22
	v_and_b32_e32 v41, 0xffff0000, v41
	v_add_f32_e32 v18, v18, v20
	v_mul_f32_e32 v20, v24, v24
	v_and_b32_e32 v37, 0xffff0000, v37
	v_add_f32_e32 v25, v25, v41
	v_fmac_f32_e32 v20, v23, v23
	v_add_f32_e32 v33, v33, v37
	v_add_f32_e32 v18, v20, v18
	v_mul_f32_e32 v20, v25, v25
	v_fmac_f32_e32 v20, v33, v33
	v_and_b32_e32 v42, 0xffff0000, v42
	v_add_f32_e32 v18, v20, v18
	v_mul_f32_e32 v20, v46, v46
	v_and_b32_e32 v38, 0xffff0000, v38
	v_add_f32_e32 v19, v19, v42
	v_fmac_f32_e32 v20, v26, v26
	v_add_f32_e32 v27, v27, v38
	v_add_f32_e32 v18, v20, v18
	v_mul_f32_e32 v20, v19, v19
	v_lshlrev_b32_e32 v47, 16, v39
	v_fmac_f32_e32 v20, v27, v27
	v_and_b32_e32 v43, 0xffff0000, v43
	v_add_f32_e32 v28, v28, v47
	v_add_f32_e32 v18, v20, v18
	v_mul_f32_e32 v20, v32, v32
	v_and_b32_e32 v39, 0xffff0000, v39
	v_add_f32_e32 v36, v21, v43
	v_fmac_f32_e32 v20, v28, v28
	v_add_f32_e32 v29, v29, v39
	v_add_f32_e32 v18, v20, v18
	v_mul_f32_e32 v20, v36, v36
	v_fmac_f32_e32 v20, v29, v29
	v_add_f32_e32 v18, v20, v18
	v_lshl_add_u32 v37, v34, 11, v148
	v_cvt_pk_bf16_f32 v20, v30, v22
	v_cvt_pk_bf16_f32 v21, v23, v33
	v_cvt_pk_bf16_f32 v22, v26, v27
	v_cvt_pk_bf16_f32 v23, v28, v29
	s_waitcnt lgkmcnt(0)
	buffer_store_dwordx4 v[252:255], v247, s[64:67], 0 offen offset:256 sc1
	v_add_u32_e32 v247, v246, v37
	ds_bpermute_b32 v252, v245, v20
	ds_bpermute_b32 v253, v245, v21
	ds_bpermute_b32 v254, v245, v22
	ds_bpermute_b32 v255, v245, v23
	s_nop 1
	v_cvt_pk_bf16_f32 v20, v44, v31
	v_cvt_pk_bf16_f32 v21, v24, v25
	v_cvt_pk_bf16_f32 v22, v46, v19
	v_mov_b32_e32 v19, v18
	s_nop 1
	v_permlane16_swap_b32 v19, v18
	v_cvt_pk_bf16_f32 v23, v32, v36
	s_waitcnt lgkmcnt(0)
	buffer_store_dwordx4 v[252:255], v247, s[64:67], 0 offen sc1
	v_add_u32_e32 v247, v246, v37
	ds_bpermute_b32 v252, v245, v20
	ds_bpermute_b32 v253, v245, v21
	ds_bpermute_b32 v254, v245, v22
	ds_bpermute_b32 v255, v245, v23
	s_waitcnt lgkmcnt(0)
	v_add_f32_e32 v18, v18, v19
	v_mov_b32_e32 v19, v18
	s_nop 1
	v_permlane32_swap_b32 v19, v18
	s_and_saveexec_b64 s[2:3], s[40:41]
	s_cbranch_execz .LBB0_950
	v_lshl_add_u64 v[20:21], v[34:35], 2, s[0:1]
	s_waitcnt lgkmcnt(0)
	v_add_f32_e32 v18, v18, v19
	global_atomic_add_f32 v[20:21], v18, off
.LBB0_950:
	s_or_b64 exec, exec, s[2:3]
	v_add_u32_e32 v18, 0xb0, v142
	s_waitcnt lgkmcnt(0)
	v_ashrrev_i32_e32 v19, 31, v18
	v_lshlrev_b64 v[20:21], 11, v[18:19]
	v_lshl_add_u64 v[20:21], s[58:59], 0, v[20:21]
	v_lshl_add_u64 v[24:25], v[140:141], 1, v[20:21]
	s_waitcnt vmcnt(21)
	v_mov_b64_e32 v[20:21], v[230:231]
	v_mov_b64_e32 v[22:23], v[232:233]
	s_nop 0
	v_mov_b64_e32 v[24:25], v[234:235]
	v_mov_b64_e32 v[26:27], v[236:237]
	v_lshl_add_u32 v28, v18, 11, v148
	v_lshlrev_b32_e32 v29, 16, v20
	v_lshlrev_b32_e32 v33, 16, v24
	v_and_b32_e32 v24, 0xffff0000, v24
	v_and_b32_e32 v20, 0xffff0000, v20
	v_lshlrev_b32_e32 v30, 16, v21
	v_and_b32_e32 v21, 0xffff0000, v21
	v_lshlrev_b32_e32 v34, 16, v25
	v_lshlrev_b32_e32 v35, 16, v26
	v_and_b32_e32 v26, 0xffff0000, v26
	v_lshlrev_b32_e32 v36, 16, v27
	v_and_b32_e32 v27, 0xffff0000, v27
	v_add_f32_e32 v6, v6, v33
	v_add_f32_e32 v7, v7, v24
	v_lshlrev_b32_e32 v31, 16, v22
	v_and_b32_e32 v22, 0xffff0000, v22
	v_and_b32_e32 v25, 0xffff0000, v25
	v_add_f32_e32 v14, v14, v29
	v_add_f32_e32 v15, v15, v20
	v_add_f32_e32 v20, v3, v26
	v_add_f32_e32 v3, v16, v30
	v_add_f32_e32 v8, v8, v34
	v_add_f32_e32 v16, v4, v36
	v_add_f32_e32 v4, v17, v21
	v_add_f32_e32 v17, v5, v27
	v_mul_f32_e32 v5, v6, v6
	v_mul_f32_e32 v21, v7, v7
	v_lshlrev_b32_e32 v32, 16, v23
	v_and_b32_e32 v23, 0xffff0000, v23
	v_add_f32_e32 v11, v11, v22
	v_add_f32_e32 v9, v9, v25
	v_mul_f32_e32 v22, v8, v8
	v_fmac_f32_e32 v5, v14, v14
	v_fmac_f32_e32 v21, v15, v15
	v_add_f32_e32 v29, v2, v35
	v_add_f32_e32 v13, v13, v23
	v_mul_f32_e32 v23, v9, v9
	v_fmac_f32_e32 v22, v3, v3
	v_add_f32_e32 v5, v5, v21
	v_add_f32_e32 v10, v10, v31
	v_mul_f32_e32 v24, v29, v29
	v_fmac_f32_e32 v23, v4, v4
	v_add_f32_e32 v5, v22, v5
	v_mul_f32_e32 v25, v20, v20
	v_fmac_f32_e32 v24, v10, v10
	v_add_f32_e32 v5, v23, v5
	v_add_f32_e32 v12, v12, v32
	v_mul_f32_e32 v26, v16, v16
	v_fmac_f32_e32 v25, v11, v11
	v_add_f32_e32 v5, v24, v5
	v_mul_f32_e32 v27, v17, v17
	v_fmac_f32_e32 v26, v12, v12
	v_add_f32_e32 v5, v25, v5
	v_fmac_f32_e32 v27, v13, v13
	v_add_f32_e32 v5, v26, v5
	v_cvt_pk_bf16_f32 v2, v14, v15
	v_add_f32_e32 v14, v27, v5
	v_mov_b32_e32 v15, v14
	s_nop 1
	v_permlane16_swap_b32 v15, v14
	v_cvt_pk_bf16_f32 v3, v3, v4
	v_cvt_pk_bf16_f32 v4, v10, v11
	v_cvt_pk_bf16_f32 v5, v12, v13
	s_waitcnt lgkmcnt(0)
	buffer_store_dwordx4 v[252:255], v247, s[64:67], 0 offen offset:256 sc1
	v_add_u32_e32 v247, v246, v28
	ds_bpermute_b32 v252, v245, v2
	ds_bpermute_b32 v253, v245, v3
	ds_bpermute_b32 v254, v245, v4
	ds_bpermute_b32 v255, v245, v5
	s_waitcnt lgkmcnt(0)
	s_nop 0
	v_add_f32_e32 v2, v14, v15
	v_mov_b32_e32 v3, v2
	s_nop 1
	v_permlane32_swap_b32 v3, v2
	v_cvt_pk_bf16_f32 v4, v6, v7
	v_cvt_pk_bf16_f32 v5, v8, v9
	v_cvt_pk_bf16_f32 v6, v29, v20
	v_cvt_pk_bf16_f32 v7, v16, v17
	s_waitcnt lgkmcnt(0)
	buffer_store_dwordx4 v[252:255], v247, s[64:67], 0 offen sc1
	v_add_u32_e32 v247, v246, v28
	ds_bpermute_b32 v252, v245, v4
	ds_bpermute_b32 v253, v245, v5
	ds_bpermute_b32 v254, v245, v6
	ds_bpermute_b32 v255, v245, v7
	s_waitcnt lgkmcnt(0)
	buffer_store_dwordx4 v[252:255], v247, s[64:67], 0 offen offset:256 sc1
	s_and_saveexec_b64 s[2:3], s[40:41]
	s_cbranch_execz .LBB0_927
	v_lshl_add_u64 v[4:5], v[18:19], 2, s[0:1]
	s_waitcnt lgkmcnt(0)
	v_add_f32_e32 v2, v2, v3
	global_atomic_add_f32 v[4:5], v2, off
	s_branch .LBB0_927
